# v16 + HGRN in-proj GEMM phase: half of the blocks (block_id bit 3) start ~4.5us late (s_sleep 127) so the two halves' write-through epilogue store bursts do not coincide
# speedup vs baseline: 1.0085x; 1.0011x over previous
.LBB0_385:
	v_readlane_b32 s68, v252, 32
	s_mov_b64 s[6:7], 0x1c00000
	s_and_b64 vcc, exec, s[4:5]
	v_readlane_b32 s72, v252, 36
	v_readlane_b32 s73, v252, 37
	v_readlane_b32 s74, v252, 38
	v_readlane_b32 s75, v252, 39
	v_readlane_b32 s76, v252, 40
	v_readlane_b32 s77, v252, 41
	v_readlane_b32 s78, v252, 42
	v_readlane_b32 s79, v252, 43
	v_readlane_b32 s80, v252, 44
	v_readlane_b32 s81, v252, 45
	v_readlane_b32 s69, v252, 33
	v_readlane_b32 s70, v252, 34
	v_readlane_b32 s71, v252, 35
	v_readlane_b32 s82, v252, 46
	v_readlane_b32 s83, v252, 47
	s_cbranch_vccz .LBB0_1088
	s_bitcmp1_b32 s2, 3
	s_cbranch_scc0 .Lg0_nodelay
	s_sleep 127
.Lg0_nodelay:
	v_readlane_b32 s6, v255, 21
	s_cmp_eq_u32 s6, 0
	s_mov_b64 s[4:5], s[24:25]
	v_readlane_b32 s7, v255, 22
	s_cselect_b64 s[10:11], -1, 0
	s_cmp_lg_u32 s6, 0
	s_cselect_b64 s[6:7], -1, 0
	s_add_u32 s8, s4, 0xc50c000
	v_readlane_b32 s70, v253, 53
	s_addc_u32 s9, s5, 0
	s_and_b64 vcc, exec, s[10:11]
	v_readlane_b32 s71, v253, 54
	v_readlane_b32 s82, v255, 15
	s_mov_b32 s83, 0x800000
	s_cbranch_vccnz .LBB0_390
